# lag-kernel build loops of ssm_build_mef now request four state blocks per trip before reducing the first (was two)
# speedup vs baseline: 1.0026x; 1.0026x over previous
; __device__ __forceinline__ void ssm_build_mef(const Params& p, const Ctx& c, int l) {
;     ...
;   for (long i = c.gtid; i < 32L * 2 * 32 * 256; i += c.nthr) { const int hp = (int)(i & 15), h = (int)((i >> 4) & 15), j = (int)((i >> 8) & 31), gd = (int)(i >> 13), d = gd & 1, g = gd >> 1;
;     const size_t ci = ((size_t)((l * 2 + d) * 32 + g) * 16 + h) * 64; const float2* pw = PW + ((size_t)gd * 33 + j) * 64; const float2* bb = BB + (size_t)gd * 64 * 16 + hp; float a = 0.f;
;     for (int pp = 0; pp < 64; ++pp) { const float cr = p.ssm_c_re[ci + pp], cim = p.ssm_c_im[ci + pp]; const float2 b = bb[pp * 16], w = pw[pp];
;       const float wr = cr * b.x - cim * b.y, wi = cr * b.y + cim * b.x; a += wr * w.x - wi * w.y; }
;     MK[i] = a; }
.LBB0_178:
	v_lshl_add_u64 v[28:29], v[18:19], 0, s[36:37]
	v_lshl_add_u64 v[32:33], s[10:11], 0, v[12:13]
	v_lshl_add_u64 v[30:31], v[16:17], 0, s[36:37]
	global_load_dwordx4 v[20:23], v[28:29], off
	global_load_dwordx4 v[24:27], v[30:31], off
	v_add_co_u32_e32 v28, vcc, 0xabcc000, v32
	v_lshl_add_u64 v[34:35], s[10:11], 0, v[14:15]
	s_nop 0
	v_addc_co_u32_e32 v29, vcc, 0, v33, vcc
	v_add_co_u32_e32 v38, vcc, 0xa9bc000, v34
	global_load_dwordx2 v[40:41], v[28:29], off
	global_load_dwordx2 v[42:43], v[28:29], off offset:128
	global_load_dwordx2 v[44:45], v[28:29], off offset:256
	global_load_dwordx2 v[46:47], v[28:29], off offset:384
	v_addc_co_u32_e32 v39, vcc, 0, v35, vcc
	v_lshl_add_u64 v[36:37], v[34:35], 0, s[20:21]
	global_load_dwordx4 v[28:31], v[38:39], off
	global_load_dwordx4 v[32:35], v[36:37], off offset:16
	s_add_u32 s36, s36, 16
	s_addc_u32 s37, s37, 0
	v_lshl_add_u64 v[12:13], v[12:13], 0, s[24:25]
	v_lshl_add_u64 v[14:15], v[14:15], 0, 32
	s_cmpk_eq_i32 s36, 0x100
	v_lshl_add_u64 v[104:105], v[18:19], 0, s[36:37]
	v_lshl_add_u64 v[108:109], s[10:11], 0, v[12:13]
	v_lshl_add_u64 v[106:107], v[16:17], 0, s[36:37]
	global_load_dwordx4 v[96:99], v[104:105], off
	global_load_dwordx4 v[100:103], v[106:107], off
	v_add_co_u32_e32 v104, vcc, 0xabcc000, v108
	v_lshl_add_u64 v[110:111], s[10:11], 0, v[14:15]
	s_nop 0
	v_addc_co_u32_e32 v105, vcc, 0, v109, vcc
	v_add_co_u32_e32 v114, vcc, 0xa9bc000, v110
	global_load_dwordx2 v[116:117], v[104:105], off
	global_load_dwordx2 v[118:119], v[104:105], off offset:128
	global_load_dwordx2 v[120:121], v[104:105], off offset:256
	global_load_dwordx2 v[122:123], v[104:105], off offset:384
	v_addc_co_u32_e32 v115, vcc, 0, v111, vcc
	v_lshl_add_u64 v[112:113], v[110:111], 0, s[20:21]
	global_load_dwordx4 v[104:107], v[114:115], off
	global_load_dwordx4 v[108:111], v[112:113], off offset:16
	s_add_u32 s36, s36, 16
	s_addc_u32 s37, s37, 0
	v_lshl_add_u64 v[12:13], v[12:13], 0, s[24:25]
	v_lshl_add_u64 v[14:15], v[14:15], 0, 32
	s_cmpk_eq_i32 s36, 0x100
	v_lshl_add_u64 v[140:141], v[18:19], 0, s[36:37]
	v_lshl_add_u64 v[144:145], s[10:11], 0, v[12:13]
	v_lshl_add_u64 v[142:143], v[16:17], 0, s[36:37]
	global_load_dwordx4 v[132:135], v[140:141], off
	global_load_dwordx4 v[136:139], v[142:143], off
	v_add_co_u32_e32 v140, vcc, 0xabcc000, v144
	v_lshl_add_u64 v[146:147], s[10:11], 0, v[14:15]
	s_nop 0
	v_addc_co_u32_e32 v141, vcc, 0, v145, vcc
	v_add_co_u32_e32 v150, vcc, 0xa9bc000, v146
	global_load_dwordx2 v[152:153], v[140:141], off
	global_load_dwordx2 v[154:155], v[140:141], off offset:128
	global_load_dwordx2 v[156:157], v[140:141], off offset:256
	global_load_dwordx2 v[158:159], v[140:141], off offset:384
	v_addc_co_u32_e32 v151, vcc, 0, v147, vcc
	v_lshl_add_u64 v[148:149], v[146:147], 0, s[20:21]
	global_load_dwordx4 v[140:143], v[150:151], off
	global_load_dwordx4 v[144:147], v[148:149], off offset:16
	s_add_u32 s36, s36, 16
	s_addc_u32 s37, s37, 0
	v_lshl_add_u64 v[12:13], v[12:13], 0, s[24:25]
	v_lshl_add_u64 v[14:15], v[14:15], 0, 32
	s_cmpk_eq_i32 s36, 0x100
	v_lshl_add_u64 v[176:177], v[18:19], 0, s[36:37]
	v_lshl_add_u64 v[180:181], s[10:11], 0, v[12:13]
	v_lshl_add_u64 v[178:179], v[16:17], 0, s[36:37]
	global_load_dwordx4 v[168:171], v[176:177], off
	global_load_dwordx4 v[172:175], v[178:179], off
	v_add_co_u32_e32 v176, vcc, 0xabcc000, v180
	v_lshl_add_u64 v[182:183], s[10:11], 0, v[14:15]
	s_nop 0
	v_addc_co_u32_e32 v177, vcc, 0, v181, vcc
	v_add_co_u32_e32 v186, vcc, 0xa9bc000, v182
	global_load_dwordx2 v[188:189], v[176:177], off
	global_load_dwordx2 v[190:191], v[176:177], off offset:128
	global_load_dwordx2 v[192:193], v[176:177], off offset:256
	global_load_dwordx2 v[194:195], v[176:177], off offset:384
	v_addc_co_u32_e32 v187, vcc, 0, v183, vcc
	v_lshl_add_u64 v[184:185], v[182:183], 0, s[20:21]
	global_load_dwordx4 v[176:179], v[186:187], off
	global_load_dwordx4 v[180:183], v[184:185], off offset:16
	s_add_u32 s36, s36, 16
	s_addc_u32 s37, s37, 0
	v_lshl_add_u64 v[12:13], v[12:13], 0, s[24:25]
	v_lshl_add_u64 v[14:15], v[14:15], 0, 32
	s_cmpk_eq_i32 s36, 0x100
	s_waitcnt vmcnt(31)
	v_mov_b32_e32 v36, v21
	s_waitcnt vmcnt(30)
	v_mov_b32_e32 v50, v27
	v_mov_b32_e32 v38, v23
	v_mov_b32_e32 v48, v23
	s_waitcnt vmcnt(29)
	v_pk_mul_f32 v[52:53], v[24:25], v[40:41] op_sel:[0,1] op_sel_hi:[0,0]
	s_waitcnt vmcnt(28)
	v_pk_mul_f32 v[24:25], v[24:25], v[42:43] op_sel:[1,1] op_sel_hi:[1,0]
	v_pk_fma_f32 v[54:55], v[20:21], v[40:41], v[52:53] neg_lo:[0,0,1] neg_hi:[0,0,1]
	v_pk_fma_f32 v[40:41], v[20:21], v[40:41], v[52:53] op_sel_hi:[0,1,1]
	s_waitcnt vmcnt(27)
	v_pk_mul_f32 v[26:27], v[26:27], v[44:45] op_sel:[0,1] op_sel_hi:[0,0]
	v_pk_fma_f32 v[36:37], v[36:37], v[42:43], v[24:25] neg_lo:[0,0,1] neg_hi:[0,0,1]
	v_pk_fma_f32 v[20:21], v[20:21], v[42:43], v[24:25] op_sel:[1,0,0]
	v_mov_b32_e32 v55, v41
	s_waitcnt vmcnt(26)
	v_pk_mul_f32 v[50:51], v[50:51], v[46:47] op_sel:[0,1] op_sel_hi:[0,0]
	v_pk_fma_f32 v[24:25], v[22:23], v[44:45], v[26:27] neg_lo:[0,0,1] neg_hi:[0,0,1]
	v_pk_fma_f32 v[22:23], v[22:23], v[44:45], v[26:27] op_sel_hi:[0,1,1]
	v_mov_b32_e32 v37, v21
	s_waitcnt vmcnt(25)
	v_pk_mul_f32 v[20:21], v[28:29], v[54:55]
	v_pk_fma_f32 v[26:27], v[38:39], v[46:47], v[50:51] neg_lo:[0,0,1] neg_hi:[0,0,1]
	v_pk_fma_f32 v[38:39], v[48:49], v[46:47], v[50:51] op_sel_hi:[0,1,1]
	v_mov_b32_e32 v25, v23
	v_pk_mul_f32 v[22:23], v[30:31], v[36:37]
	v_sub_f32_e32 v20, v20, v21
	v_mov_b32_e32 v27, v39
	s_waitcnt vmcnt(24)
	v_pk_mul_f32 v[24:25], v[32:33], v[24:25]
	v_sub_f32_e32 v21, v22, v23
	v_add_f32_e32 v6, v6, v20
	v_pk_mul_f32 v[26:27], v[34:35], v[26:27]
	v_sub_f32_e32 v22, v24, v25
	v_add_f32_e32 v6, v6, v21
	v_sub_f32_e32 v23, v26, v27
	v_add_f32_e32 v6, v6, v22
	v_add_f32_e32 v6, v6, v23
	s_waitcnt vmcnt(23)
; __device__ __forceinline__ void ssm_build_mef(const Params& p, const Ctx& c, int l) {
;     ...
;   for (long i = c.gtid; i < 32L * 2 * 32 * 256; i += c.nthr) { const int hp = (int)(i & 15), h = (int)((i >> 4) & 15), j = (int)((i >> 8) & 31), gd = (int)(i >> 13), d = gd & 1, g = gd >> 1;
;     const size_t ci = ((size_t)((l * 2 + d) * 32 + g) * 16 + h) * 64; const float2* pw = PW + ((size_t)gd * 33 + j) * 64; const float2* bb = BB + (size_t)gd * 64 * 16 + hp; float a = 0.f;
;     for (int pp = 0; pp < 64; ++pp) { const float cr = p.ssm_c_re[ci + pp], cim = p.ssm_c_im[ci + pp]; const float2 b = bb[pp * 16], w = pw[pp];
;       const float wr = cr * b.x - cim * b.y, wi = cr * b.y + cim * b.x; a += wr * w.x - wi * w.y; }
;     MK[i] = a; }
	v_mov_b32_e32 v112, v97
	s_waitcnt vmcnt(22)
	v_mov_b32_e32 v126, v103
	v_mov_b32_e32 v114, v99
	v_mov_b32_e32 v124, v99
	s_waitcnt vmcnt(21)
	v_pk_mul_f32 v[128:129], v[100:101], v[116:117] op_sel:[0,1] op_sel_hi:[0,0]
	s_waitcnt vmcnt(20)
	v_pk_mul_f32 v[100:101], v[100:101], v[118:119] op_sel:[1,1] op_sel_hi:[1,0]
	v_pk_fma_f32 v[130:131], v[96:97], v[116:117], v[128:129] neg_lo:[0,0,1] neg_hi:[0,0,1]
	v_pk_fma_f32 v[116:117], v[96:97], v[116:117], v[128:129] op_sel_hi:[0,1,1]
	s_waitcnt vmcnt(19)
	v_pk_mul_f32 v[102:103], v[102:103], v[120:121] op_sel:[0,1] op_sel_hi:[0,0]
	v_pk_fma_f32 v[112:113], v[112:113], v[118:119], v[100:101] neg_lo:[0,0,1] neg_hi:[0,0,1]
	v_pk_fma_f32 v[96:97], v[96:97], v[118:119], v[100:101] op_sel:[1,0,0]
	v_mov_b32_e32 v131, v117
	s_waitcnt vmcnt(18)
	v_pk_mul_f32 v[126:127], v[126:127], v[122:123] op_sel:[0,1] op_sel_hi:[0,0]
	v_pk_fma_f32 v[100:101], v[98:99], v[120:121], v[102:103] neg_lo:[0,0,1] neg_hi:[0,0,1]
	v_pk_fma_f32 v[98:99], v[98:99], v[120:121], v[102:103] op_sel_hi:[0,1,1]
	v_mov_b32_e32 v113, v97
	s_waitcnt vmcnt(17)
	v_pk_mul_f32 v[96:97], v[104:105], v[130:131]
	v_pk_fma_f32 v[102:103], v[114:115], v[122:123], v[126:127] neg_lo:[0,0,1] neg_hi:[0,0,1]
	v_pk_fma_f32 v[114:115], v[124:125], v[122:123], v[126:127] op_sel_hi:[0,1,1]
	v_mov_b32_e32 v101, v99
	v_pk_mul_f32 v[98:99], v[106:107], v[112:113]
	v_sub_f32_e32 v96, v96, v97
	v_mov_b32_e32 v103, v115
	s_waitcnt vmcnt(16)
	v_pk_mul_f32 v[100:101], v[108:109], v[100:101]
	v_sub_f32_e32 v97, v98, v99
	v_add_f32_e32 v6, v6, v96
	v_pk_mul_f32 v[102:103], v[110:111], v[102:103]
	v_sub_f32_e32 v98, v100, v101
	v_add_f32_e32 v6, v6, v97
	v_sub_f32_e32 v99, v102, v103
	v_add_f32_e32 v6, v6, v98
	v_add_f32_e32 v6, v6, v99
	s_waitcnt vmcnt(15)
	v_mov_b32_e32 v148, v133
	s_waitcnt vmcnt(14)
	v_mov_b32_e32 v162, v139
	v_mov_b32_e32 v150, v135
	v_mov_b32_e32 v160, v135
	s_waitcnt vmcnt(13)
	v_pk_mul_f32 v[164:165], v[136:137], v[152:153] op_sel:[0,1] op_sel_hi:[0,0]
	s_waitcnt vmcnt(12)
	v_pk_mul_f32 v[136:137], v[136:137], v[154:155] op_sel:[1,1] op_sel_hi:[1,0]
	v_pk_fma_f32 v[166:167], v[132:133], v[152:153], v[164:165] neg_lo:[0,0,1] neg_hi:[0,0,1]
	v_pk_fma_f32 v[152:153], v[132:133], v[152:153], v[164:165] op_sel_hi:[0,1,1]
	s_waitcnt vmcnt(11)
	v_pk_mul_f32 v[138:139], v[138:139], v[156:157] op_sel:[0,1] op_sel_hi:[0,0]
	v_pk_fma_f32 v[148:149], v[148:149], v[154:155], v[136:137] neg_lo:[0,0,1] neg_hi:[0,0,1]
	v_pk_fma_f32 v[132:133], v[132:133], v[154:155], v[136:137] op_sel:[1,0,0]
	v_mov_b32_e32 v167, v153
	s_waitcnt vmcnt(10)
	v_pk_mul_f32 v[162:163], v[162:163], v[158:159] op_sel:[0,1] op_sel_hi:[0,0]
	v_pk_fma_f32 v[136:137], v[134:135], v[156:157], v[138:139] neg_lo:[0,0,1] neg_hi:[0,0,1]
	v_pk_fma_f32 v[134:135], v[134:135], v[156:157], v[138:139] op_sel_hi:[0,1,1]
	v_mov_b32_e32 v149, v133
	s_waitcnt vmcnt(9)
	v_pk_mul_f32 v[132:133], v[140:141], v[166:167]
	v_pk_fma_f32 v[138:139], v[150:151], v[158:159], v[162:163] neg_lo:[0,0,1] neg_hi:[0,0,1]
	v_pk_fma_f32 v[150:151], v[160:161], v[158:159], v[162:163] op_sel_hi:[0,1,1]
	v_mov_b32_e32 v137, v135
	v_pk_mul_f32 v[134:135], v[142:143], v[148:149]
	v_sub_f32_e32 v132, v132, v133
	v_mov_b32_e32 v139, v151
	s_waitcnt vmcnt(8)
	v_pk_mul_f32 v[136:137], v[144:145], v[136:137]
	v_sub_f32_e32 v133, v134, v135
	v_add_f32_e32 v6, v6, v132
	v_pk_mul_f32 v[138:139], v[146:147], v[138:139]
	v_sub_f32_e32 v134, v136, v137
	v_add_f32_e32 v6, v6, v133
	v_sub_f32_e32 v135, v138, v139
	v_add_f32_e32 v6, v6, v134
	v_add_f32_e32 v6, v6, v135
	s_waitcnt vmcnt(7)
	v_mov_b32_e32 v184, v169
	s_waitcnt vmcnt(6)
	v_mov_b32_e32 v198, v175
	v_mov_b32_e32 v186, v171
	v_mov_b32_e32 v196, v171
	s_waitcnt vmcnt(5)
	v_pk_mul_f32 v[200:201], v[172:173], v[188:189] op_sel:[0,1] op_sel_hi:[0,0]
	s_waitcnt vmcnt(4)
	v_pk_mul_f32 v[172:173], v[172:173], v[190:191] op_sel:[1,1] op_sel_hi:[1,0]
	v_pk_fma_f32 v[202:203], v[168:169], v[188:189], v[200:201] neg_lo:[0,0,1] neg_hi:[0,0,1]
	v_pk_fma_f32 v[188:189], v[168:169], v[188:189], v[200:201] op_sel_hi:[0,1,1]
	s_waitcnt vmcnt(3)
	v_pk_mul_f32 v[174:175], v[174:175], v[192:193] op_sel:[0,1] op_sel_hi:[0,0]
	v_pk_fma_f32 v[184:185], v[184:185], v[190:191], v[172:173] neg_lo:[0,0,1] neg_hi:[0,0,1]
	v_pk_fma_f32 v[168:169], v[168:169], v[190:191], v[172:173] op_sel:[1,0,0]
	v_mov_b32_e32 v203, v189
	s_waitcnt vmcnt(2)
	v_pk_mul_f32 v[198:199], v[198:199], v[194:195] op_sel:[0,1] op_sel_hi:[0,0]
	v_pk_fma_f32 v[172:173], v[170:171], v[192:193], v[174:175] neg_lo:[0,0,1] neg_hi:[0,0,1]
	v_pk_fma_f32 v[170:171], v[170:171], v[192:193], v[174:175] op_sel_hi:[0,1,1]
	v_mov_b32_e32 v185, v169
	s_waitcnt vmcnt(1)
	v_pk_mul_f32 v[168:169], v[176:177], v[202:203]
	v_pk_fma_f32 v[174:175], v[186:187], v[194:195], v[198:199] neg_lo:[0,0,1] neg_hi:[0,0,1]
	v_pk_fma_f32 v[186:187], v[196:197], v[194:195], v[198:199] op_sel_hi:[0,1,1]
	v_mov_b32_e32 v173, v171
	v_pk_mul_f32 v[170:171], v[178:179], v[184:185]
	v_sub_f32_e32 v168, v168, v169
	v_mov_b32_e32 v175, v187
	s_waitcnt vmcnt(0)
	v_pk_mul_f32 v[172:173], v[180:181], v[172:173]
	v_sub_f32_e32 v169, v170, v171
	v_add_f32_e32 v6, v6, v168
	v_pk_mul_f32 v[174:175], v[182:183], v[174:175]
	v_sub_f32_e32 v170, v172, v173
	v_add_f32_e32 v6, v6, v169
	v_sub_f32_e32 v171, v174, v175
	v_add_f32_e32 v6, v6, v170
	v_add_f32_e32 v6, v6, v171
	s_cbranch_scc0 .LBB0_178
	v_readlane_b32 s22, v250, 2
	v_readlane_b32 s23, v250, 3
	v_lshl_add_u64 v[12:13], v[10:11], 2, s[14:15]
	v_lshl_add_u64 v[8:9], v[8:9], 0, s[18:19]
	v_lshl_add_u64 v[10:11], v[10:11], 0, s[22:23]
	v_cmp_lt_i64_e32 vcc, s[34:35], v[10:11]
	s_or_b64 s[16:17], vcc, s[16:17]
	global_store_dword v[12:13], v6, off
	s_andn2_b64 exec, exec, s[16:17]
	s_cbranch_execnz .LBB0_177
	s_or_b64 exec, exec, s[16:17]
	s_add_u32 s14, s10, 0xa9bc000
	s_addc_u32 s15, s11, 0
	s_add_u32 s4, s10, 0xabcc000
	s_addc_u32 s5, s11, 0
	s_add_u32 s6, s10, 0xc8cc000
	s_addc_u32 s7, s11, 0
	s_lshl_b64 s[0:1], s[12:13], 12
	v_lshl_add_u64 v[4:5], v[4:5], 3, s[0:1]
	s_lshl_b64 s[16:17], s[30:31], 12
	s_mov_b64 s[12:13], 0
	s_movk_i32 s0, 0x80
	v_mov_b32_e32 v7, 0
	s_mov_b64 s[18:19], 0x7ffff
	v_mov_b64_e32 v[8:9], v[0:1]

; __device__ __forceinline__ void ssm_build_mef(const Params& p, const Ctx& c, int l) {
;     ...
;   for (long i = c.gtid; i < 32L * 2 * 32 * 256; i += c.nthr) { const int hp = (int)(i & 15), h = (int)((i >> 4) & 15), j = (int)((i >> 8) & 31), gd = (int)(i >> 13), d = gd & 1, g = gd >> 1;
;     const size_t ci = ((size_t)((l * 2 + d) * 32 + g) * 16 + h) * 64; const float2* pw = PW + ((size_t)gd * 33 + j) * 64; const float2* bb = BB + (size_t)gd * 64 * 16 + hp; float a = 0.f;
;     for (int pp = 0; pp < 64; ++pp) { const float cr = p.ssm_c_re[ci + pp], cim = p.ssm_c_im[ci + pp]; const float2 b = bb[pp * 16], w = pw[pp];
;       const float wr = cr * b.x - cim * b.y, wi = cr * b.y + cim * b.x; a += wr * w.x - wi * w.y; }
;     MK[i] = a; }
.LBB0_967:
	v_lshl_add_u64 v[16:17], v[14:15], 0, s[62:63]
	global_load_dwordx4 v[22:25], v[16:17], off
	v_lshl_add_u64 v[16:17], v[12:13], 0, s[62:63]
	global_load_dwordx4 v[26:29], v[16:17], off
	v_lshl_add_u64 v[16:17], s[54:55], 0, v[8:9]
	v_add_co_u32_e32 v16, vcc, 0xac4c000, v16
	v_lshl_add_u64 v[30:31], s[54:55], 0, v[10:11]
	s_nop 0
	v_addc_co_u32_e32 v17, vcc, 0, v17, vcc
	global_load_dwordx2 v[38:39], v[16:17], off
	global_load_dwordx2 v[60:61], v[16:17], off offset:128
	global_load_dwordx2 v[62:63], v[16:17], off offset:256
	global_load_dwordx2 v[64:65], v[16:17], off offset:384
	s_mov_b64 s[0:1], 0xaac4000
	v_lshl_add_u64 v[34:35], v[30:31], 0, s[0:1]
	v_add_co_u32_e32 v30, vcc, 0xaac4000, v30
	s_add_u32 s62, s62, 16
	s_nop 0
	v_addc_co_u32_e32 v31, vcc, 0, v31, vcc
	global_load_dwordx4 v[30:33], v[30:31], off
	s_nop 0
	global_load_dwordx4 v[34:37], v[34:35], off offset:16
	s_mov_b64 s[0:1], 0x200
	s_addc_u32 s63, s63, 0
	v_lshl_add_u64 v[8:9], v[8:9], 0, s[0:1]
	v_lshl_add_u64 v[10:11], v[10:11], 0, 32
	s_cmpk_eq_i32 s62, 0x100
	v_lshl_add_u64 v[70:71], v[14:15], 0, s[62:63]
	global_load_dwordx4 v[72:75], v[70:71], off
	v_lshl_add_u64 v[70:71], v[12:13], 0, s[62:63]
	global_load_dwordx4 v[76:79], v[70:71], off
	v_lshl_add_u64 v[70:71], s[54:55], 0, v[8:9]
	v_add_co_u32_e32 v70, vcc, 0xac4c000, v70
	v_lshl_add_u64 v[80:81], s[54:55], 0, v[10:11]
	s_nop 0
	v_addc_co_u32_e32 v71, vcc, 0, v71, vcc
	global_load_dwordx2 v[88:89], v[70:71], off
	global_load_dwordx2 v[94:95], v[70:71], off offset:128
	global_load_dwordx2 v[96:97], v[70:71], off offset:256
	global_load_dwordx2 v[98:99], v[70:71], off offset:384
	s_mov_b64 s[0:1], 0xaac4000
	v_lshl_add_u64 v[84:85], v[80:81], 0, s[0:1]
	v_add_co_u32_e32 v80, vcc, 0xaac4000, v80
	s_add_u32 s62, s62, 16
	s_nop 0
	v_addc_co_u32_e32 v81, vcc, 0, v81, vcc
	global_load_dwordx4 v[80:83], v[80:81], off
	s_nop 0
	global_load_dwordx4 v[84:87], v[84:85], off offset:16
	s_mov_b64 s[0:1], 0x200
	s_addc_u32 s63, s63, 0
	v_lshl_add_u64 v[8:9], v[8:9], 0, s[0:1]
	v_lshl_add_u64 v[10:11], v[10:11], 0, 32
	s_cmpk_eq_i32 s62, 0x100
	v_lshl_add_u64 v[102:103], v[14:15], 0, s[62:63]
	global_load_dwordx4 v[104:107], v[102:103], off
	v_lshl_add_u64 v[102:103], v[12:13], 0, s[62:63]
	global_load_dwordx4 v[108:111], v[102:103], off
	v_lshl_add_u64 v[102:103], s[54:55], 0, v[8:9]
	v_add_co_u32_e32 v102, vcc, 0xac4c000, v102
	v_lshl_add_u64 v[112:113], s[54:55], 0, v[10:11]
	s_nop 0
	v_addc_co_u32_e32 v103, vcc, 0, v103, vcc
	global_load_dwordx2 v[120:121], v[102:103], off
	global_load_dwordx2 v[126:127], v[102:103], off offset:128
	global_load_dwordx2 v[128:129], v[102:103], off offset:256
	global_load_dwordx2 v[130:131], v[102:103], off offset:384
	s_mov_b64 s[0:1], 0xaac4000
	v_lshl_add_u64 v[116:117], v[112:113], 0, s[0:1]
	v_add_co_u32_e32 v112, vcc, 0xaac4000, v112
	s_add_u32 s62, s62, 16
	s_nop 0
	v_addc_co_u32_e32 v113, vcc, 0, v113, vcc
	global_load_dwordx4 v[112:115], v[112:113], off
	s_nop 0
	global_load_dwordx4 v[116:119], v[116:117], off offset:16
	s_mov_b64 s[0:1], 0x200
	s_addc_u32 s63, s63, 0
	v_lshl_add_u64 v[8:9], v[8:9], 0, s[0:1]
	v_lshl_add_u64 v[10:11], v[10:11], 0, 32
	s_cmpk_eq_i32 s62, 0x100
	v_lshl_add_u64 v[134:135], v[14:15], 0, s[62:63]
	global_load_dwordx4 v[136:139], v[134:135], off
	v_lshl_add_u64 v[134:135], v[12:13], 0, s[62:63]
	global_load_dwordx4 v[140:143], v[134:135], off
	v_lshl_add_u64 v[134:135], s[54:55], 0, v[8:9]
	v_add_co_u32_e32 v134, vcc, 0xac4c000, v134
	v_lshl_add_u64 v[144:145], s[54:55], 0, v[10:11]
	s_nop 0
	v_addc_co_u32_e32 v135, vcc, 0, v135, vcc
	global_load_dwordx2 v[152:153], v[134:135], off
	global_load_dwordx2 v[158:159], v[134:135], off offset:128
	global_load_dwordx2 v[160:161], v[134:135], off offset:256
	global_load_dwordx2 v[162:163], v[134:135], off offset:384
	s_mov_b64 s[0:1], 0xaac4000
	v_lshl_add_u64 v[148:149], v[144:145], 0, s[0:1]
	v_add_co_u32_e32 v144, vcc, 0xaac4000, v144
	s_add_u32 s62, s62, 16
	s_nop 0
	v_addc_co_u32_e32 v145, vcc, 0, v145, vcc
	global_load_dwordx4 v[144:147], v[144:145], off
	s_nop 0
	global_load_dwordx4 v[148:151], v[148:149], off offset:16
	s_mov_b64 s[0:1], 0x200
	s_addc_u32 s63, s63, 0
	v_lshl_add_u64 v[8:9], v[8:9], 0, s[0:1]
	v_lshl_add_u64 v[10:11], v[10:11], 0, 32
	s_cmpk_eq_i32 s62, 0x100
	s_waitcnt vmcnt(29)
	v_pk_mul_f32 v[40:41], v[26:27], v[38:39] op_sel:[0,1] op_sel_hi:[0,0]
	v_pk_fma_f32 v[42:43], v[22:23], v[38:39], v[40:41] neg_lo:[0,0,1] neg_hi:[0,0,1]
	v_pk_fma_f32 v[38:39], v[22:23], v[38:39], v[40:41] op_sel_hi:[0,1,1]
	v_mov_b32_e32 v43, v39
	v_mov_b32_e32 v38, v23
	s_waitcnt vmcnt(25)
	v_pk_mul_f32 v[30:31], v[30:31], v[42:43]
	s_nop 0
	v_sub_f32_e32 v30, v30, v31
	v_add_f32_e32 v1, v1, v30
	s_waitcnt vmcnt(24)
	v_mov_b64_e32 v[30:31], v[60:61]
	v_pk_mul_f32 v[26:27], v[26:27], v[30:31] op_sel:[1,1] op_sel_hi:[1,0]
	s_nop 0
	v_pk_fma_f32 v[38:39], v[38:39], v[30:31], v[26:27] neg_lo:[0,0,1] neg_hi:[0,0,1]
	v_pk_fma_f32 v[22:23], v[22:23], v[30:31], v[26:27] op_sel:[1,0,0]
	s_nop 0
	v_mov_b32_e32 v39, v23
	v_pk_mul_f32 v[22:23], v[32:33], v[38:39]
	s_nop 0
	v_sub_f32_e32 v22, v22, v23
	v_add_f32_e32 v1, v1, v22
	s_waitcnt vmcnt(24)
	v_mov_b64_e32 v[22:23], v[62:63]
	v_pk_mul_f32 v[26:27], v[28:29], v[22:23] op_sel:[0,1] op_sel_hi:[0,0]
	v_mov_b64_e32 v[16:17], v[64:65]
	v_pk_fma_f32 v[30:31], v[24:25], v[22:23], v[26:27] neg_lo:[0,0,1] neg_hi:[0,0,1]
	v_pk_fma_f32 v[22:23], v[24:25], v[22:23], v[26:27] op_sel_hi:[0,1,1]
	v_mov_b32_e32 v31, v23
	v_pk_mul_f32 v[22:23], v[34:35], v[30:31]
	v_mov_b32_e32 v26, v29
	v_sub_f32_e32 v22, v22, v23
	v_add_f32_e32 v1, v1, v22
	v_mov_b32_e32 v22, v25
	v_mov_b32_e32 v24, v25
	s_waitcnt vmcnt(24)
; __device__ __forceinline__ void ssm_build_mef(const Params& p, const Ctx& c, int l) {
;     ...
;   for (long i = c.gtid; i < 32L * 2 * 32 * 256; i += c.nthr) { const int hp = (int)(i & 15), h = (int)((i >> 4) & 15), j = (int)((i >> 8) & 31), gd = (int)(i >> 13), d = gd & 1, g = gd >> 1;
;     const size_t ci = ((size_t)((l * 2 + d) * 32 + g) * 16 + h) * 64; const float2* pw = PW + ((size_t)gd * 33 + j) * 64; const float2* bb = BB + (size_t)gd * 64 * 16 + hp; float a = 0.f;
;     for (int pp = 0; pp < 64; ++pp) { const float cr = p.ssm_c_re[ci + pp], cim = p.ssm_c_im[ci + pp]; const float2 b = bb[pp * 16], w = pw[pp];
;       const float wr = cr * b.x - cim * b.y, wi = cr * b.y + cim * b.x; a += wr * w.x - wi * w.y; }
;     MK[i] = a; }
	v_pk_mul_f32 v[26:27], v[26:27], v[16:17] op_sel:[0,1] op_sel_hi:[0,0]
	v_pk_fma_f32 v[22:23], v[22:23], v[16:17], v[26:27] neg_lo:[0,0,1] neg_hi:[0,0,1]
	v_pk_fma_f32 v[16:17], v[24:25], v[16:17], v[26:27] op_sel_hi:[0,1,1]
	v_mov_b32_e32 v23, v17
	v_pk_mul_f32 v[16:17], v[36:37], v[22:23]
	s_nop 0
	v_sub_f32_e32 v16, v16, v17
	v_add_f32_e32 v1, v1, v16
	s_waitcnt vmcnt(21)
	v_pk_mul_f32 v[90:91], v[76:77], v[88:89] op_sel:[0,1] op_sel_hi:[0,0]
	v_pk_fma_f32 v[92:93], v[72:73], v[88:89], v[90:91] neg_lo:[0,0,1] neg_hi:[0,0,1]
	v_pk_fma_f32 v[88:89], v[72:73], v[88:89], v[90:91] op_sel_hi:[0,1,1]
	v_mov_b32_e32 v93, v89
	v_mov_b32_e32 v88, v73
	s_waitcnt vmcnt(17)
	v_pk_mul_f32 v[80:81], v[80:81], v[92:93]
	s_nop 0
	v_sub_f32_e32 v80, v80, v81
	v_add_f32_e32 v1, v1, v80
	s_waitcnt vmcnt(16)
	v_mov_b64_e32 v[80:81], v[94:95]
	v_pk_mul_f32 v[76:77], v[76:77], v[80:81] op_sel:[1,1] op_sel_hi:[1,0]
	s_nop 0
	v_pk_fma_f32 v[88:89], v[88:89], v[80:81], v[76:77] neg_lo:[0,0,1] neg_hi:[0,0,1]
	v_pk_fma_f32 v[72:73], v[72:73], v[80:81], v[76:77] op_sel:[1,0,0]
	s_nop 0
	v_mov_b32_e32 v89, v73
	v_pk_mul_f32 v[72:73], v[82:83], v[88:89]
	s_nop 0
	v_sub_f32_e32 v72, v72, v73
	v_add_f32_e32 v1, v1, v72
	s_waitcnt vmcnt(16)
	v_mov_b64_e32 v[72:73], v[96:97]
	v_pk_mul_f32 v[76:77], v[78:79], v[72:73] op_sel:[0,1] op_sel_hi:[0,0]
	v_mov_b64_e32 v[70:71], v[98:99]
	v_pk_fma_f32 v[80:81], v[74:75], v[72:73], v[76:77] neg_lo:[0,0,1] neg_hi:[0,0,1]
	v_pk_fma_f32 v[72:73], v[74:75], v[72:73], v[76:77] op_sel_hi:[0,1,1]
	v_mov_b32_e32 v81, v73
	v_pk_mul_f32 v[72:73], v[84:85], v[80:81]
	v_mov_b32_e32 v76, v79
	v_sub_f32_e32 v72, v72, v73
	v_add_f32_e32 v1, v1, v72
	v_mov_b32_e32 v72, v75
	v_mov_b32_e32 v74, v75
	s_waitcnt vmcnt(16)
	v_pk_mul_f32 v[76:77], v[76:77], v[70:71] op_sel:[0,1] op_sel_hi:[0,0]
	v_pk_fma_f32 v[72:73], v[72:73], v[70:71], v[76:77] neg_lo:[0,0,1] neg_hi:[0,0,1]
	v_pk_fma_f32 v[70:71], v[74:75], v[70:71], v[76:77] op_sel_hi:[0,1,1]
	v_mov_b32_e32 v73, v71
	v_pk_mul_f32 v[70:71], v[86:87], v[72:73]
	s_nop 0
	v_sub_f32_e32 v70, v70, v71
	v_add_f32_e32 v1, v1, v70
	s_waitcnt vmcnt(13)
	v_pk_mul_f32 v[122:123], v[108:109], v[120:121] op_sel:[0,1] op_sel_hi:[0,0]
	v_pk_fma_f32 v[124:125], v[104:105], v[120:121], v[122:123] neg_lo:[0,0,1] neg_hi:[0,0,1]
	v_pk_fma_f32 v[120:121], v[104:105], v[120:121], v[122:123] op_sel_hi:[0,1,1]
	v_mov_b32_e32 v125, v121
	v_mov_b32_e32 v120, v105
	s_waitcnt vmcnt(9)
	v_pk_mul_f32 v[112:113], v[112:113], v[124:125]
	s_nop 0
	v_sub_f32_e32 v112, v112, v113
	v_add_f32_e32 v1, v1, v112
	s_waitcnt vmcnt(8)
	v_mov_b64_e32 v[112:113], v[126:127]
	v_pk_mul_f32 v[108:109], v[108:109], v[112:113] op_sel:[1,1] op_sel_hi:[1,0]
	s_nop 0
	v_pk_fma_f32 v[120:121], v[120:121], v[112:113], v[108:109] neg_lo:[0,0,1] neg_hi:[0,0,1]
	v_pk_fma_f32 v[104:105], v[104:105], v[112:113], v[108:109] op_sel:[1,0,0]
	s_nop 0
	v_mov_b32_e32 v121, v105
	v_pk_mul_f32 v[104:105], v[114:115], v[120:121]
	s_nop 0
	v_sub_f32_e32 v104, v104, v105
	v_add_f32_e32 v1, v1, v104
	s_waitcnt vmcnt(8)
	v_mov_b64_e32 v[104:105], v[128:129]
	v_pk_mul_f32 v[108:109], v[110:111], v[104:105] op_sel:[0,1] op_sel_hi:[0,0]
	v_mov_b64_e32 v[102:103], v[130:131]
	v_pk_fma_f32 v[112:113], v[106:107], v[104:105], v[108:109] neg_lo:[0,0,1] neg_hi:[0,0,1]
	v_pk_fma_f32 v[104:105], v[106:107], v[104:105], v[108:109] op_sel_hi:[0,1,1]
	v_mov_b32_e32 v113, v105
	v_pk_mul_f32 v[104:105], v[116:117], v[112:113]
	v_mov_b32_e32 v108, v111
	v_sub_f32_e32 v104, v104, v105
	v_add_f32_e32 v1, v1, v104
	v_mov_b32_e32 v104, v107
	v_mov_b32_e32 v106, v107
	s_waitcnt vmcnt(8)
	v_pk_mul_f32 v[108:109], v[108:109], v[102:103] op_sel:[0,1] op_sel_hi:[0,0]
	v_pk_fma_f32 v[104:105], v[104:105], v[102:103], v[108:109] neg_lo:[0,0,1] neg_hi:[0,0,1]
	v_pk_fma_f32 v[102:103], v[106:107], v[102:103], v[108:109] op_sel_hi:[0,1,1]
	v_mov_b32_e32 v105, v103
	v_pk_mul_f32 v[102:103], v[118:119], v[104:105]
	s_nop 0
	v_sub_f32_e32 v102, v102, v103
	v_add_f32_e32 v1, v1, v102
	s_waitcnt vmcnt(5)
	v_pk_mul_f32 v[154:155], v[140:141], v[152:153] op_sel:[0,1] op_sel_hi:[0,0]
	v_pk_fma_f32 v[156:157], v[136:137], v[152:153], v[154:155] neg_lo:[0,0,1] neg_hi:[0,0,1]
	v_pk_fma_f32 v[152:153], v[136:137], v[152:153], v[154:155] op_sel_hi:[0,1,1]
	v_mov_b32_e32 v157, v153
	v_mov_b32_e32 v152, v137
	s_waitcnt vmcnt(1)
	v_pk_mul_f32 v[144:145], v[144:145], v[156:157]
	s_nop 0
	v_sub_f32_e32 v144, v144, v145
	v_add_f32_e32 v1, v1, v144
	s_waitcnt vmcnt(0)
	v_mov_b64_e32 v[144:145], v[158:159]
	v_pk_mul_f32 v[140:141], v[140:141], v[144:145] op_sel:[1,1] op_sel_hi:[1,0]
	s_nop 0
	v_pk_fma_f32 v[152:153], v[152:153], v[144:145], v[140:141] neg_lo:[0,0,1] neg_hi:[0,0,1]
	v_pk_fma_f32 v[136:137], v[136:137], v[144:145], v[140:141] op_sel:[1,0,0]
	s_nop 0
	v_mov_b32_e32 v153, v137
	v_pk_mul_f32 v[136:137], v[146:147], v[152:153]
	s_nop 0
	v_sub_f32_e32 v136, v136, v137
	v_add_f32_e32 v1, v1, v136
	s_waitcnt vmcnt(0)
	v_mov_b64_e32 v[136:137], v[160:161]
	v_pk_mul_f32 v[140:141], v[142:143], v[136:137] op_sel:[0,1] op_sel_hi:[0,0]
	v_mov_b64_e32 v[134:135], v[162:163]
	v_pk_fma_f32 v[144:145], v[138:139], v[136:137], v[140:141] neg_lo:[0,0,1] neg_hi:[0,0,1]
	v_pk_fma_f32 v[136:137], v[138:139], v[136:137], v[140:141] op_sel_hi:[0,1,1]
	v_mov_b32_e32 v145, v137
	v_pk_mul_f32 v[136:137], v[148:149], v[144:145]
	v_mov_b32_e32 v140, v143
	v_sub_f32_e32 v136, v136, v137
	v_add_f32_e32 v1, v1, v136
	v_mov_b32_e32 v136, v139
	v_mov_b32_e32 v138, v139
	s_waitcnt vmcnt(0)
	v_pk_mul_f32 v[140:141], v[140:141], v[134:135] op_sel:[0,1] op_sel_hi:[0,0]
	v_pk_fma_f32 v[136:137], v[136:137], v[134:135], v[140:141] neg_lo:[0,0,1] neg_hi:[0,0,1]
	v_pk_fma_f32 v[134:135], v[138:139], v[134:135], v[140:141] op_sel_hi:[0,1,1]
	v_mov_b32_e32 v137, v135
	v_pk_mul_f32 v[134:135], v[150:151], v[136:137]
	s_nop 0
	v_sub_f32_e32 v134, v134, v135
	v_add_f32_e32 v1, v1, v134
	s_cbranch_scc0 .LBB0_967
	v_lshl_add_u64 v[8:9], v[6:7], 2, s[56:57]
	v_lshl_add_u64 v[6:7], v[6:7], 0, s[22:23]
	v_readlane_b32 s0, v250, 5
	v_cmp_lt_i64_e32 vcc, s[70:71], v[6:7]
	v_readlane_b32 s1, v250, 6
	s_or_b64 s[60:61], vcc, s[60:61]
	global_store_dword v[8:9], v1, off
	v_lshl_add_u64 v[4:5], v[4:5], 0, s[0:1]
	s_andn2_b64 exec, exec, s[60:61]
	s_cbranch_execnz .LBB0_966
	s_or_b64 exec, exec, s[60:61]
	s_add_u32 s56, s54, 0xaac4000
	s_addc_u32 s57, s55, 0
	s_add_u32 s12, s54, 0xac4c000
	s_addc_u32 s13, s55, 0
	s_add_u32 s14, s54, 0xc8cc000
	s_addc_u32 s15, s55, 0
	s_lshl_b64 s[0:1], s[58:59], 12
	v_lshl_add_u64 v[22:23], v[2:3], 3, s[0:1]
	s_mov_b64 s[58:59], 0
	v_mov_b64_e32 v[24:25], v[18:19]
